# grid barrier: dropped redundant wbl2/inv fences (7 per-flag release fences on last arriver, duplicate fences on arrive/leader/exit)
# speedup vs baseline: 1.0189x; 1.0189x over previous
; DI void grid_bar2(unsigned* bar, unsigned epoch, unsigned per_group) {
;     ...
;     while (__hip_atomic_load(bar + (9u + x) * 32, __ATOMIC_RELAXED, __HIP_MEMORY_SCOPE_AGENT) < epoch) __builtin_amdgcn_s_sleep(1);
;     __threadfence();
;     asm volatile("s_waitcnt vmcnt(0)" ::: "memory");
.LBB0_2:
	s_nop 0
	buffer_inv sc1
	s_waitcnt vmcnt(0)

; DI int my_tid() { int t = threadIdx.x; asm volatile("" : "+v"(t)); return t; }
; DI void grid_bar2(unsigned* bar, unsigned epoch, unsigned per_group) {
;   __syncthreads();
;   if (my_tid() == 0) {
;     __threadfence();
;     const unsigned x = blockIdx.x & 7u;
;     const unsigned prev = __hip_atomic_fetch_add(bar + x * 32, 1u, __ATOMIC_ACQ_REL, __HIP_MEMORY_SCOPE_AGENT);
;     if (prev == per_group - 1u) {
;       __hip_atomic_store(bar + x * 32, 0u, __ATOMIC_RELAXED, __HIP_MEMORY_SCOPE_AGENT);
;       const unsigned pg = __hip_atomic_fetch_add(bar + 256, 1u, __ATOMIC_ACQ_REL, __HIP_MEMORY_SCOPE_AGENT);
;       if (pg == 7u) {
;         __hip_atomic_store(bar + 256, 0u, __ATOMIC_RELAXED, __HIP_MEMORY_SCOPE_AGENT);
;         for (unsigned j = 0; j < 8u; ++j) __hip_atomic_store(bar + (9u + j) * 32, epoch, __ATOMIC_RELEASE, __HIP_MEMORY_SCOPE_AGENT);
;       }
;     }
.LBB0_948:
	s_and_b64 vcc, exec, s[0:1]
	s_cbranch_vccz .LBB0_4
	v_mov_b32_e32 v0, v152
	s_waitcnt lgkmcnt(0)
	s_barrier
	s_nop 0
	v_cmp_eq_u32_e32 vcc, 0, v0
	s_and_saveexec_b64 s[0:1], vcc
	s_cbranch_execz .LBB0_3
	s_mov_b64 s[2:3], exec
	v_mbcnt_lo_u32_b32 v0, s2, 0
	v_mbcnt_hi_u32_b32 v0, s3, v0
	v_cmp_eq_u32_e32 vcc, 0, v0
	buffer_wbl2 sc1
	s_waitcnt vmcnt(0)
	s_nop 0
	s_and_saveexec_b64 s[4:5], vcc
	s_cbranch_execz .LBB0_952
	s_bcnt1_i32_b64 s2, s[2:3]
	v_mov_b32_e32 v2, s2
	v_readlane_b32 s2, v246, 36
	v_readlane_b32 s3, v246, 37
	s_nop 0
	s_nop 3
	global_atomic_add v2, v1, v2, s[2:3] sc0
	s_waitcnt vmcnt(0)
	s_nop 0
.LBB0_952:
	s_or_b64 exec, exec, s[4:5]
	v_readlane_b32 s2, v245, 52
	s_sub_i32 s9, s2, s70
	v_readfirstlane_b32 s2, v2
	s_nop 1
	v_add_u32_e32 v0, s2, v0
	v_readlane_b32 s2, v246, 38
	s_nop 1
	v_cmp_eq_u32_e32 vcc, s2, v0
	s_and_saveexec_b64 s[2:3], vcc
	s_cbranch_execz .LBB0_957
	s_mov_b64 s[4:5], exec
	v_mbcnt_lo_u32_b32 v0, s4, 0
	v_readlane_b32 s6, v246, 36
	v_mbcnt_hi_u32_b32 v0, s5, v0
	v_readlane_b32 s7, v246, 37
	v_cmp_eq_u32_e32 vcc, 0, v0
	s_nop 3
	global_store_dword v1, v1, s[6:7] sc1
	s_and_saveexec_b64 s[6:7], vcc
	s_cbranch_execz .LBB0_955
	s_bcnt1_i32_b64 s4, s[4:5]
	v_mov_b32_e32 v2, s4
	v_readlane_b32 s4, v246, 39
	v_readlane_b32 s5, v246, 40
	s_nop 0
	s_waitcnt vmcnt(0)
	s_nop 2
	global_atomic_add v2, v1, v2, s[4:5] sc0
	s_waitcnt vmcnt(0)
	s_nop 0
.LBB0_955:
	s_or_b64 exec, exec, s[6:7]
	v_readfirstlane_b32 s4, v2
	s_nop 1
	v_add_u32_e32 v0, s4, v0
	v_cmp_eq_u32_e32 vcc, 7, v0
	s_and_b64 exec, exec, vcc
	s_cbranch_execz .LBB0_957
	v_readlane_b32 s4, v246, 39
	v_readlane_b32 s5, v246, 40
	v_mov_b32_e32 v0, s9
	s_nop 3
	global_store_dword v1, v1, s[4:5] sc1
	v_readlane_b32 s4, v246, 41
	v_readlane_b32 s5, v246, 42
	buffer_wbl2 sc1
	s_waitcnt vmcnt(0)
	s_nop 2
	global_store_dword v1, v0, s[4:5] sc1
	v_readlane_b32 s4, v246, 43
	v_readlane_b32 s5, v246, 44
	s_nop 0
	s_nop 0
	s_nop 2
	global_store_dword v1, v0, s[4:5] sc1
	v_readlane_b32 s4, v246, 45
	v_readlane_b32 s5, v246, 46
	s_nop 0
	s_nop 0
	s_nop 2
	global_store_dword v1, v0, s[4:5] sc1
	v_readlane_b32 s4, v246, 47
	v_readlane_b32 s5, v246, 48
	s_nop 0
	s_nop 0
	s_nop 2
	global_store_dword v1, v0, s[4:5] sc1
	v_readlane_b32 s4, v246, 49
	v_readlane_b32 s5, v246, 50
	s_nop 0
	s_nop 0
	s_nop 2
	global_store_dword v1, v0, s[4:5] sc1
	v_readlane_b32 s4, v246, 51
	v_readlane_b32 s5, v246, 52
	s_nop 0
	s_nop 0
	s_nop 2
	global_store_dword v1, v0, s[4:5] sc1
	v_readlane_b32 s4, v246, 53
	v_readlane_b32 s5, v246, 54
	s_nop 0
	s_nop 0
	s_nop 2
	global_store_dword v1, v0, s[4:5] sc1
	v_readlane_b32 s4, v246, 55
	v_readlane_b32 s5, v246, 56
	s_nop 0
	s_nop 0
	s_nop 2
	global_store_dword v1, v0, s[4:5] sc1
